# rewrote out-proj residual epilogue (mode 1): permlane16 swap + dwordx4 loads/stores, counted vmcnt
# speedup vs baseline: 1.0057x; 1.0057x over previous
.LBB0_53:
	v_lshl_add_u32 v194, s46, 8, v235
	v_lshl_or_b32 v192, s45, 8, v237
	v_ashrrev_i32_e32 v195, 31, v194
	v_lshlrev_b64 v[128:129], 11, v[194:195]
	v_ashrrev_i32_e32 v193, 31, v192
	v_lshl_add_u64 v[128:129], v[128:129], 0, v[192:193]
	v_lshlrev_b64 v[130:131], 1, v[128:129]
	s_and_b64 vcc, exec, s[10:11]
	v_lshl_add_u64 v[198:199], s[94:95], 0, v[130:131]
	v_lshl_add_u64 v[196:197], s[8:9], 0, v[130:131]
	s_cbranch_vccz .LBB0_71
	v_and_b32_e32 v230, 16, v225
	v_readlane_b32 s26, v255, 35
	v_readlane_b32 s27, v255, 36
	v_lshrrev_b32_e32 v231, 1, v230
	v_add_u32_e32 v230, v230, v231
	v_add_co_u32_e32 v164, vcc, v198, v230
	s_lshl_b32 s2, s45, 4
	v_addc_co_u32_e32 v165, vcc, 0, v199, vcc
	v_add_co_u32_e32 v166, vcc, v196, v230
	s_lshl_b32 s3, s41, 2
	v_addc_co_u32_e32 v167, vcc, 0, v197, vcc
	s_add_i32 s2, s2, s3
	v_mov_b32_e32 v168, v164
	v_mov_b32_e32 v169, v165
	v_mov_b32_e32 v170, v166
	v_mov_b32_e32 v171, v167
	global_load_dwordx4 v[132:135], v[168:169], off
	global_load_dwordx4 v[136:139], v[170:171], off
	global_load_dwordx4 v[140:143], v[168:169], off offset:256
	global_load_dwordx4 v[144:147], v[170:171], off offset:256
	v_add_co_u32_e32 v168, vcc, 0x10000, v164
	v_addc_co_u32_e32 v169, vcc, 0, v165, vcc
	v_add_co_u32_e32 v170, vcc, 0x10000, v166
	v_addc_co_u32_e32 v171, vcc, 0, v167, vcc
	global_load_dwordx4 v[148:151], v[168:169], off
	global_load_dwordx4 v[152:155], v[170:171], off
	global_load_dwordx4 v[156:159], v[168:169], off offset:256
	global_load_dwordx4 v[160:163], v[170:171], off offset:256
	v_add_co_u32_e32 v168, vcc, 0x20000, v164
	v_addc_co_u32_e32 v169, vcc, 0, v165, vcc
	v_add_co_u32_e32 v170, vcc, 0x20000, v166
	v_addc_co_u32_e32 v171, vcc, 0, v167, vcc
	global_load_dwordx4 v[200:203], v[168:169], off
	global_load_dwordx4 v[204:207], v[170:171], off
	global_load_dwordx4 v[208:211], v[168:169], off offset:256
	global_load_dwordx4 v[212:215], v[170:171], off offset:256
	v_lshlrev_b32_e32 v230, 7, v194
	v_add_u32_e32 v230, s2, v230
	v_mov_b32_e32 v173, s27
	v_add_co_u32_e32 v172, vcc, s26, v230
	v_addc_co_u32_e32 v173, vcc, 0, v173, vcc
	v_mov_b32_e32 v128, v164
	v_mov_b32_e32 v129, v165
	v_mov_b32_e32 v130, v166
	v_mov_b32_e32 v131, v167
	v_permlane16_swap_b32_e32 v124, v120
	v_permlane16_swap_b32_e32 v125, v121
	v_permlane16_swap_b32_e32 v126, v122
	v_permlane16_swap_b32_e32 v127, v123
	s_waitcnt vmcnt(11)
	v_lshlrev_b32_e32 v216, 16, v132
	v_and_b32_e32 v217, 0xffff0000, v132
	s_waitcnt vmcnt(10)
	v_lshlrev_b32_e32 v218, 16, v136
	v_and_b32_e32 v219, 0xffff0000, v136
	v_pk_add_f32 v[216:217], v[216:217], v[218:219]
	v_pk_add_f32 v[124:125], v[216:217], v[124:125]
	v_lshlrev_b32_e32 v216, 16, v133
	v_and_b32_e32 v217, 0xffff0000, v133
	v_lshlrev_b32_e32 v218, 16, v137
	v_and_b32_e32 v219, 0xffff0000, v137
	v_pk_add_f32 v[216:217], v[216:217], v[218:219]
	v_pk_add_f32 v[126:127], v[216:217], v[126:127]
	v_lshlrev_b32_e32 v216, 16, v134
	v_and_b32_e32 v217, 0xffff0000, v134
	v_lshlrev_b32_e32 v218, 16, v138
	v_and_b32_e32 v219, 0xffff0000, v138
	v_pk_add_f32 v[216:217], v[216:217], v[218:219]
	v_pk_add_f32 v[120:121], v[216:217], v[120:121]
	v_lshlrev_b32_e32 v216, 16, v135
	v_and_b32_e32 v217, 0xffff0000, v135
	v_lshlrev_b32_e32 v218, 16, v139
	v_and_b32_e32 v219, 0xffff0000, v139
	v_pk_add_f32 v[216:217], v[216:217], v[218:219]
	v_pk_add_f32 v[122:123], v[216:217], v[122:123]
	v_cvt_pk_bf16_f32 v132, v124, v125
	v_cvt_pk_bf16_f32 v133, v126, v127
	v_cvt_pk_bf16_f32 v134, v120, v121
	v_cvt_pk_bf16_f32 v135, v122, v123
	global_store_dwordx4 v[128:129], v[132:135], off
	v_lshlrev_b32_e32 v216, 16, v132
	v_and_b32_e32 v217, 0xffff0000, v132
	v_pk_add_f32 v[216:217], v[124:125], v[216:217] neg_lo:[0,1] neg_hi:[0,1]
	v_pk_mul_f32 v[228:229], v[124:125], v[124:125]
	v_cvt_pk_bf16_f32 v136, v216, v217
	v_lshlrev_b32_e32 v216, 16, v133
	v_and_b32_e32 v217, 0xffff0000, v133
	v_pk_add_f32 v[216:217], v[126:127], v[216:217] neg_lo:[0,1] neg_hi:[0,1]
	v_pk_fma_f32 v[228:229], v[126:127], v[126:127], v[228:229]
	v_cvt_pk_bf16_f32 v137, v216, v217
	v_lshlrev_b32_e32 v216, 16, v134
	v_and_b32_e32 v217, 0xffff0000, v134
	v_pk_add_f32 v[216:217], v[120:121], v[216:217] neg_lo:[0,1] neg_hi:[0,1]
	v_pk_fma_f32 v[228:229], v[120:121], v[120:121], v[228:229]
	v_cvt_pk_bf16_f32 v138, v216, v217
	v_lshlrev_b32_e32 v216, 16, v135
	v_and_b32_e32 v217, 0xffff0000, v135
	v_pk_add_f32 v[216:217], v[122:123], v[216:217] neg_lo:[0,1] neg_hi:[0,1]
	v_pk_fma_f32 v[228:229], v[122:123], v[122:123], v[228:229]
	v_cvt_pk_bf16_f32 v139, v216, v217
	global_store_dwordx4 v[130:131], v[136:139], off
	v_permlane16_swap_b32_e32 v116, v112
	v_permlane16_swap_b32_e32 v117, v113
	v_permlane16_swap_b32_e32 v118, v114
	v_permlane16_swap_b32_e32 v119, v115
	s_waitcnt vmcnt(11)
	v_lshlrev_b32_e32 v216, 16, v140
	v_and_b32_e32 v217, 0xffff0000, v140
	s_waitcnt vmcnt(10)
	v_lshlrev_b32_e32 v218, 16, v144
	v_and_b32_e32 v219, 0xffff0000, v144
	v_pk_add_f32 v[216:217], v[216:217], v[218:219]
	v_pk_add_f32 v[116:117], v[216:217], v[116:117]
	v_lshlrev_b32_e32 v216, 16, v141
	v_and_b32_e32 v217, 0xffff0000, v141
	v_lshlrev_b32_e32 v218, 16, v145
	v_and_b32_e32 v219, 0xffff0000, v145
	v_pk_add_f32 v[216:217], v[216:217], v[218:219]
	v_pk_add_f32 v[118:119], v[216:217], v[118:119]
	v_lshlrev_b32_e32 v216, 16, v142
	v_and_b32_e32 v217, 0xffff0000, v142
	v_lshlrev_b32_e32 v218, 16, v146
	v_and_b32_e32 v219, 0xffff0000, v146
	v_pk_add_f32 v[216:217], v[216:217], v[218:219]
	v_pk_add_f32 v[112:113], v[216:217], v[112:113]
	v_lshlrev_b32_e32 v216, 16, v143
	v_and_b32_e32 v217, 0xffff0000, v143
	v_lshlrev_b32_e32 v218, 16, v147
	v_and_b32_e32 v219, 0xffff0000, v147
	v_pk_add_f32 v[216:217], v[216:217], v[218:219]
	v_pk_add_f32 v[114:115], v[216:217], v[114:115]
	v_cvt_pk_bf16_f32 v140, v116, v117
	v_cvt_pk_bf16_f32 v141, v118, v119
	v_cvt_pk_bf16_f32 v142, v112, v113
	v_cvt_pk_bf16_f32 v143, v114, v115
	global_store_dwordx4 v[128:129], v[140:143], off offset:256
	v_lshlrev_b32_e32 v216, 16, v140
	v_and_b32_e32 v217, 0xffff0000, v140
	v_pk_add_f32 v[216:217], v[116:117], v[216:217] neg_lo:[0,1] neg_hi:[0,1]
	v_pk_fma_f32 v[228:229], v[116:117], v[116:117], v[228:229]
	v_cvt_pk_bf16_f32 v144, v216, v217
	v_lshlrev_b32_e32 v216, 16, v141
	v_and_b32_e32 v217, 0xffff0000, v141
	v_pk_add_f32 v[216:217], v[118:119], v[216:217] neg_lo:[0,1] neg_hi:[0,1]
	v_pk_fma_f32 v[228:229], v[118:119], v[118:119], v[228:229]
	v_cvt_pk_bf16_f32 v145, v216, v217
	v_lshlrev_b32_e32 v216, 16, v142
	v_and_b32_e32 v217, 0xffff0000, v142
	v_pk_add_f32 v[216:217], v[112:113], v[216:217] neg_lo:[0,1] neg_hi:[0,1]
	v_pk_fma_f32 v[228:229], v[112:113], v[112:113], v[228:229]
	v_cvt_pk_bf16_f32 v146, v216, v217
	v_lshlrev_b32_e32 v216, 16, v143
	v_and_b32_e32 v217, 0xffff0000, v143
	v_pk_add_f32 v[216:217], v[114:115], v[216:217] neg_lo:[0,1] neg_hi:[0,1]
	v_pk_fma_f32 v[228:229], v[114:115], v[114:115], v[228:229]
	v_cvt_pk_bf16_f32 v147, v216, v217
	global_store_dwordx4 v[130:131], v[144:147], off offset:256
	v_add_f32_e32 v230, v228, v229
	v_mov_b32_e32 v231, v230
	s_nop 1
	v_permlane16_swap_b32_e32 v231, v230
	v_add_f32_e32 v230, v230, v231
	v_mov_b32_e32 v231, v230
	s_nop 1
	v_permlane32_swap_b32_e32 v231, v230
	v_add_f32_e32 v230, v230, v231
	v_mov_b32_e32 v174, v172
	v_mov_b32_e32 v175, v173
	s_and_saveexec_b64 s[24:25], s[14:15]
	global_store_dword v[174:175], v230, off
	s_mov_b64 exec, s[24:25]
	v_add_co_u32_e32 v168, vcc, 0x30000, v164
	v_addc_co_u32_e32 v169, vcc, 0, v165, vcc
	v_add_co_u32_e32 v170, vcc, 0x30000, v166
	v_addc_co_u32_e32 v171, vcc, 0, v167, vcc
	global_load_dwordx4 v[132:135], v[168:169], off
	global_load_dwordx4 v[136:139], v[170:171], off
	global_load_dwordx4 v[140:143], v[168:169], off offset:256
	global_load_dwordx4 v[144:147], v[170:171], off offset:256
	v_add_co_u32_e32 v128, vcc, 0x10000, v164
	v_addc_co_u32_e32 v129, vcc, 0, v165, vcc
	v_add_co_u32_e32 v130, vcc, 0x10000, v166
	v_addc_co_u32_e32 v131, vcc, 0, v167, vcc
	v_permlane16_swap_b32_e32 v108, v104
	v_permlane16_swap_b32_e32 v109, v105
	v_permlane16_swap_b32_e32 v110, v106
	v_permlane16_swap_b32_e32 v111, v107
	s_waitcnt vmcnt(16)
	v_lshlrev_b32_e32 v216, 16, v148
	v_and_b32_e32 v217, 0xffff0000, v148
	s_waitcnt vmcnt(15)
	v_lshlrev_b32_e32 v218, 16, v152
	v_and_b32_e32 v219, 0xffff0000, v152
	v_pk_add_f32 v[216:217], v[216:217], v[218:219]
	v_pk_add_f32 v[108:109], v[216:217], v[108:109]
	v_lshlrev_b32_e32 v216, 16, v149
	v_and_b32_e32 v217, 0xffff0000, v149
	v_lshlrev_b32_e32 v218, 16, v153
	v_and_b32_e32 v219, 0xffff0000, v153
	v_pk_add_f32 v[216:217], v[216:217], v[218:219]
	v_pk_add_f32 v[110:111], v[216:217], v[110:111]
	v_lshlrev_b32_e32 v216, 16, v150
	v_and_b32_e32 v217, 0xffff0000, v150
	v_lshlrev_b32_e32 v218, 16, v154
	v_and_b32_e32 v219, 0xffff0000, v154
	v_pk_add_f32 v[216:217], v[216:217], v[218:219]
	v_pk_add_f32 v[104:105], v[216:217], v[104:105]
	v_lshlrev_b32_e32 v216, 16, v151
	v_and_b32_e32 v217, 0xffff0000, v151
	v_lshlrev_b32_e32 v218, 16, v155
	v_and_b32_e32 v219, 0xffff0000, v155
	v_pk_add_f32 v[216:217], v[216:217], v[218:219]
	v_pk_add_f32 v[106:107], v[216:217], v[106:107]
	v_cvt_pk_bf16_f32 v148, v108, v109
	v_cvt_pk_bf16_f32 v149, v110, v111
	v_cvt_pk_bf16_f32 v150, v104, v105
	v_cvt_pk_bf16_f32 v151, v106, v107
	global_store_dwordx4 v[128:129], v[148:151], off
	v_lshlrev_b32_e32 v216, 16, v148
	v_and_b32_e32 v217, 0xffff0000, v148
	v_pk_add_f32 v[216:217], v[108:109], v[216:217] neg_lo:[0,1] neg_hi:[0,1]
	v_pk_mul_f32 v[228:229], v[108:109], v[108:109]
	v_cvt_pk_bf16_f32 v152, v216, v217
	v_lshlrev_b32_e32 v216, 16, v149
	v_and_b32_e32 v217, 0xffff0000, v149
	v_pk_add_f32 v[216:217], v[110:111], v[216:217] neg_lo:[0,1] neg_hi:[0,1]
	v_pk_fma_f32 v[228:229], v[110:111], v[110:111], v[228:229]
	v_cvt_pk_bf16_f32 v153, v216, v217
	v_lshlrev_b32_e32 v216, 16, v150
	v_and_b32_e32 v217, 0xffff0000, v150
	v_pk_add_f32 v[216:217], v[104:105], v[216:217] neg_lo:[0,1] neg_hi:[0,1]
	v_pk_fma_f32 v[228:229], v[104:105], v[104:105], v[228:229]
	v_cvt_pk_bf16_f32 v154, v216, v217
	v_lshlrev_b32_e32 v216, 16, v151
	v_and_b32_e32 v217, 0xffff0000, v151
	v_pk_add_f32 v[216:217], v[106:107], v[216:217] neg_lo:[0,1] neg_hi:[0,1]
	v_pk_fma_f32 v[228:229], v[106:107], v[106:107], v[228:229]
	v_cvt_pk_bf16_f32 v155, v216, v217
	global_store_dwordx4 v[130:131], v[152:155], off
	v_permlane16_swap_b32_e32 v100, v96
	v_permlane16_swap_b32_e32 v101, v97
	v_permlane16_swap_b32_e32 v102, v98
	v_permlane16_swap_b32_e32 v103, v99
	s_waitcnt vmcnt(16)
	v_lshlrev_b32_e32 v216, 16, v156
	v_and_b32_e32 v217, 0xffff0000, v156
	s_waitcnt vmcnt(15)
	v_lshlrev_b32_e32 v218, 16, v160
	v_and_b32_e32 v219, 0xffff0000, v160
	v_pk_add_f32 v[216:217], v[216:217], v[218:219]
	v_pk_add_f32 v[100:101], v[216:217], v[100:101]
	v_lshlrev_b32_e32 v216, 16, v157
	v_and_b32_e32 v217, 0xffff0000, v157
	v_lshlrev_b32_e32 v218, 16, v161
	v_and_b32_e32 v219, 0xffff0000, v161
	v_pk_add_f32 v[216:217], v[216:217], v[218:219]
	v_pk_add_f32 v[102:103], v[216:217], v[102:103]
	v_lshlrev_b32_e32 v216, 16, v158
	v_and_b32_e32 v217, 0xffff0000, v158
	v_lshlrev_b32_e32 v218, 16, v162
	v_and_b32_e32 v219, 0xffff0000, v162
	v_pk_add_f32 v[216:217], v[216:217], v[218:219]
	v_pk_add_f32 v[96:97], v[216:217], v[96:97]
	v_lshlrev_b32_e32 v216, 16, v159
	v_and_b32_e32 v217, 0xffff0000, v159
	v_lshlrev_b32_e32 v218, 16, v163
	v_and_b32_e32 v219, 0xffff0000, v163
	v_pk_add_f32 v[216:217], v[216:217], v[218:219]
	v_pk_add_f32 v[98:99], v[216:217], v[98:99]
	v_cvt_pk_bf16_f32 v156, v100, v101
	v_cvt_pk_bf16_f32 v157, v102, v103
	v_cvt_pk_bf16_f32 v158, v96, v97
	v_cvt_pk_bf16_f32 v159, v98, v99
	global_store_dwordx4 v[128:129], v[156:159], off offset:256
	v_lshlrev_b32_e32 v216, 16, v156
	v_and_b32_e32 v217, 0xffff0000, v156
	v_pk_add_f32 v[216:217], v[100:101], v[216:217] neg_lo:[0,1] neg_hi:[0,1]
	v_pk_fma_f32 v[228:229], v[100:101], v[100:101], v[228:229]
	v_cvt_pk_bf16_f32 v160, v216, v217
	v_lshlrev_b32_e32 v216, 16, v157
	v_and_b32_e32 v217, 0xffff0000, v157
	v_pk_add_f32 v[216:217], v[102:103], v[216:217] neg_lo:[0,1] neg_hi:[0,1]
	v_pk_fma_f32 v[228:229], v[102:103], v[102:103], v[228:229]
	v_cvt_pk_bf16_f32 v161, v216, v217
	v_lshlrev_b32_e32 v216, 16, v158
	v_and_b32_e32 v217, 0xffff0000, v158
	v_pk_add_f32 v[216:217], v[96:97], v[216:217] neg_lo:[0,1] neg_hi:[0,1]
	v_pk_fma_f32 v[228:229], v[96:97], v[96:97], v[228:229]
	v_cvt_pk_bf16_f32 v162, v216, v217
	v_lshlrev_b32_e32 v216, 16, v159
	v_and_b32_e32 v217, 0xffff0000, v159
	v_pk_add_f32 v[216:217], v[98:99], v[216:217] neg_lo:[0,1] neg_hi:[0,1]
	v_pk_fma_f32 v[228:229], v[98:99], v[98:99], v[228:229]
	v_cvt_pk_bf16_f32 v163, v216, v217
	global_store_dwordx4 v[130:131], v[160:163], off offset:256
	v_add_f32_e32 v230, v228, v229
	v_mov_b32_e32 v231, v230
	s_nop 1
	v_permlane16_swap_b32_e32 v231, v230
	v_add_f32_e32 v230, v230, v231
	v_mov_b32_e32 v231, v230
	s_nop 1
	v_permlane32_swap_b32_e32 v231, v230
	v_add_f32_e32 v230, v230, v231
	v_add_co_u32_e32 v174, vcc, 0x800, v172
	v_addc_co_u32_e32 v175, vcc, 0, v173, vcc
	s_and_saveexec_b64 s[24:25], s[14:15]
	global_store_dword v[174:175], v230, off
	s_mov_b64 exec, s[24:25]
	v_add_co_u32_e32 v168, vcc, 0x80000, v164
	v_addc_co_u32_e32 v169, vcc, 0, v165, vcc
	v_add_co_u32_e32 v170, vcc, 0x80000, v166
	v_addc_co_u32_e32 v171, vcc, 0, v167, vcc
	global_load_dwordx4 v[148:151], v[168:169], off
	global_load_dwordx4 v[152:155], v[170:171], off
	global_load_dwordx4 v[156:159], v[168:169], off offset:256
	global_load_dwordx4 v[160:163], v[170:171], off offset:256
	v_add_co_u32_e32 v128, vcc, 0x20000, v164
	v_addc_co_u32_e32 v129, vcc, 0, v165, vcc
	v_add_co_u32_e32 v130, vcc, 0x20000, v166
	v_addc_co_u32_e32 v131, vcc, 0, v167, vcc
	v_permlane16_swap_b32_e32 v92, v88
	v_permlane16_swap_b32_e32 v93, v89
	v_permlane16_swap_b32_e32 v94, v90
	v_permlane16_swap_b32_e32 v95, v91
	s_waitcnt vmcnt(21)
	v_lshlrev_b32_e32 v216, 16, v200
	v_and_b32_e32 v217, 0xffff0000, v200
	s_waitcnt vmcnt(20)
	v_lshlrev_b32_e32 v218, 16, v204
	v_and_b32_e32 v219, 0xffff0000, v204
	v_pk_add_f32 v[216:217], v[216:217], v[218:219]
	v_pk_add_f32 v[92:93], v[216:217], v[92:93]
	v_lshlrev_b32_e32 v216, 16, v201
	v_and_b32_e32 v217, 0xffff0000, v201
	v_lshlrev_b32_e32 v218, 16, v205
	v_and_b32_e32 v219, 0xffff0000, v205
	v_pk_add_f32 v[216:217], v[216:217], v[218:219]
	v_pk_add_f32 v[94:95], v[216:217], v[94:95]
	v_lshlrev_b32_e32 v216, 16, v202
	v_and_b32_e32 v217, 0xffff0000, v202
	v_lshlrev_b32_e32 v218, 16, v206
	v_and_b32_e32 v219, 0xffff0000, v206
	v_pk_add_f32 v[216:217], v[216:217], v[218:219]
	v_pk_add_f32 v[88:89], v[216:217], v[88:89]
	v_lshlrev_b32_e32 v216, 16, v203
	v_and_b32_e32 v217, 0xffff0000, v203
	v_lshlrev_b32_e32 v218, 16, v207
	v_and_b32_e32 v219, 0xffff0000, v207
	v_pk_add_f32 v[216:217], v[216:217], v[218:219]
	v_pk_add_f32 v[90:91], v[216:217], v[90:91]
	v_cvt_pk_bf16_f32 v200, v92, v93
	v_cvt_pk_bf16_f32 v201, v94, v95
	v_cvt_pk_bf16_f32 v202, v88, v89
	v_cvt_pk_bf16_f32 v203, v90, v91
	global_store_dwordx4 v[128:129], v[200:203], off
	v_lshlrev_b32_e32 v216, 16, v200
	v_and_b32_e32 v217, 0xffff0000, v200
	v_pk_add_f32 v[216:217], v[92:93], v[216:217] neg_lo:[0,1] neg_hi:[0,1]
	v_pk_mul_f32 v[228:229], v[92:93], v[92:93]
	v_cvt_pk_bf16_f32 v204, v216, v217
	v_lshlrev_b32_e32 v216, 16, v201
	v_and_b32_e32 v217, 0xffff0000, v201
	v_pk_add_f32 v[216:217], v[94:95], v[216:217] neg_lo:[0,1] neg_hi:[0,1]
	v_pk_fma_f32 v[228:229], v[94:95], v[94:95], v[228:229]
	v_cvt_pk_bf16_f32 v205, v216, v217
	v_lshlrev_b32_e32 v216, 16, v202
	v_and_b32_e32 v217, 0xffff0000, v202
	v_pk_add_f32 v[216:217], v[88:89], v[216:217] neg_lo:[0,1] neg_hi:[0,1]
	v_pk_fma_f32 v[228:229], v[88:89], v[88:89], v[228:229]
	v_cvt_pk_bf16_f32 v206, v216, v217
	v_lshlrev_b32_e32 v216, 16, v203
	v_and_b32_e32 v217, 0xffff0000, v203
	v_pk_add_f32 v[216:217], v[90:91], v[216:217] neg_lo:[0,1] neg_hi:[0,1]
	v_pk_fma_f32 v[228:229], v[90:91], v[90:91], v[228:229]
	v_cvt_pk_bf16_f32 v207, v216, v217
	global_store_dwordx4 v[130:131], v[204:207], off
	v_permlane16_swap_b32_e32 v84, v80
	v_permlane16_swap_b32_e32 v85, v81
	v_permlane16_swap_b32_e32 v86, v82
	v_permlane16_swap_b32_e32 v87, v83
	s_waitcnt vmcnt(21)
	v_lshlrev_b32_e32 v216, 16, v208
	v_and_b32_e32 v217, 0xffff0000, v208
	s_waitcnt vmcnt(20)
	v_lshlrev_b32_e32 v218, 16, v212
	v_and_b32_e32 v219, 0xffff0000, v212
	v_pk_add_f32 v[216:217], v[216:217], v[218:219]
	v_pk_add_f32 v[84:85], v[216:217], v[84:85]
	v_lshlrev_b32_e32 v216, 16, v209
	v_and_b32_e32 v217, 0xffff0000, v209
	v_lshlrev_b32_e32 v218, 16, v213
	v_and_b32_e32 v219, 0xffff0000, v213
	v_pk_add_f32 v[216:217], v[216:217], v[218:219]
	v_pk_add_f32 v[86:87], v[216:217], v[86:87]
	v_lshlrev_b32_e32 v216, 16, v210
	v_and_b32_e32 v217, 0xffff0000, v210
	v_lshlrev_b32_e32 v218, 16, v214
	v_and_b32_e32 v219, 0xffff0000, v214
	v_pk_add_f32 v[216:217], v[216:217], v[218:219]
	v_pk_add_f32 v[80:81], v[216:217], v[80:81]
	v_lshlrev_b32_e32 v216, 16, v211
	v_and_b32_e32 v217, 0xffff0000, v211
	v_lshlrev_b32_e32 v218, 16, v215
	v_and_b32_e32 v219, 0xffff0000, v215
	v_pk_add_f32 v[216:217], v[216:217], v[218:219]
	v_pk_add_f32 v[82:83], v[216:217], v[82:83]
	v_cvt_pk_bf16_f32 v208, v84, v85
	v_cvt_pk_bf16_f32 v209, v86, v87
	v_cvt_pk_bf16_f32 v210, v80, v81
	v_cvt_pk_bf16_f32 v211, v82, v83
	global_store_dwordx4 v[128:129], v[208:211], off offset:256
	v_lshlrev_b32_e32 v216, 16, v208
	v_and_b32_e32 v217, 0xffff0000, v208
	v_pk_add_f32 v[216:217], v[84:85], v[216:217] neg_lo:[0,1] neg_hi:[0,1]
	v_pk_fma_f32 v[228:229], v[84:85], v[84:85], v[228:229]
	v_cvt_pk_bf16_f32 v212, v216, v217
	v_lshlrev_b32_e32 v216, 16, v209
	v_and_b32_e32 v217, 0xffff0000, v209
	v_pk_add_f32 v[216:217], v[86:87], v[216:217] neg_lo:[0,1] neg_hi:[0,1]
	v_pk_fma_f32 v[228:229], v[86:87], v[86:87], v[228:229]
	v_cvt_pk_bf16_f32 v213, v216, v217
	v_lshlrev_b32_e32 v216, 16, v210
	v_and_b32_e32 v217, 0xffff0000, v210
	v_pk_add_f32 v[216:217], v[80:81], v[216:217] neg_lo:[0,1] neg_hi:[0,1]
	v_pk_fma_f32 v[228:229], v[80:81], v[80:81], v[228:229]
	v_cvt_pk_bf16_f32 v214, v216, v217
	v_lshlrev_b32_e32 v216, 16, v211
	v_and_b32_e32 v217, 0xffff0000, v211
	v_pk_add_f32 v[216:217], v[82:83], v[216:217] neg_lo:[0,1] neg_hi:[0,1]
	v_pk_fma_f32 v[228:229], v[82:83], v[82:83], v[228:229]
	v_cvt_pk_bf16_f32 v215, v216, v217
	global_store_dwordx4 v[130:131], v[212:215], off offset:256
	v_add_f32_e32 v230, v228, v229
	v_mov_b32_e32 v231, v230
	s_nop 1
	v_permlane16_swap_b32_e32 v231, v230
	v_add_f32_e32 v230, v230, v231
	v_mov_b32_e32 v231, v230
	s_nop 1
	v_permlane32_swap_b32_e32 v231, v230
	v_add_f32_e32 v230, v230, v231
	v_add_co_u32_e32 v174, vcc, 0x1000, v172
	v_addc_co_u32_e32 v175, vcc, 0, v173, vcc
	s_and_saveexec_b64 s[24:25], s[14:15]
	global_store_dword v[174:175], v230, off
	s_mov_b64 exec, s[24:25]
	v_add_co_u32_e32 v168, vcc, 0x90000, v164
	v_addc_co_u32_e32 v169, vcc, 0, v165, vcc
	v_add_co_u32_e32 v170, vcc, 0x90000, v166
	v_addc_co_u32_e32 v171, vcc, 0, v167, vcc
	global_load_dwordx4 v[200:203], v[168:169], off
	global_load_dwordx4 v[204:207], v[170:171], off
	global_load_dwordx4 v[208:211], v[168:169], off offset:256
	global_load_dwordx4 v[212:215], v[170:171], off offset:256
	v_add_co_u32_e32 v128, vcc, 0x30000, v164
	v_addc_co_u32_e32 v129, vcc, 0, v165, vcc
	v_add_co_u32_e32 v130, vcc, 0x30000, v166
	v_addc_co_u32_e32 v131, vcc, 0, v167, vcc
	v_permlane16_swap_b32_e32 v76, v72
	v_permlane16_swap_b32_e32 v77, v73
	v_permlane16_swap_b32_e32 v78, v74
	v_permlane16_swap_b32_e32 v79, v75
	s_waitcnt vmcnt(21)
	v_lshlrev_b32_e32 v216, 16, v132
	v_and_b32_e32 v217, 0xffff0000, v132
	s_waitcnt vmcnt(20)
	v_lshlrev_b32_e32 v218, 16, v136
	v_and_b32_e32 v219, 0xffff0000, v136
	v_pk_add_f32 v[216:217], v[216:217], v[218:219]
	v_pk_add_f32 v[76:77], v[216:217], v[76:77]
	v_lshlrev_b32_e32 v216, 16, v133
	v_and_b32_e32 v217, 0xffff0000, v133
	v_lshlrev_b32_e32 v218, 16, v137
	v_and_b32_e32 v219, 0xffff0000, v137
	v_pk_add_f32 v[216:217], v[216:217], v[218:219]
	v_pk_add_f32 v[78:79], v[216:217], v[78:79]
	v_lshlrev_b32_e32 v216, 16, v134
	v_and_b32_e32 v217, 0xffff0000, v134
	v_lshlrev_b32_e32 v218, 16, v138
	v_and_b32_e32 v219, 0xffff0000, v138
	v_pk_add_f32 v[216:217], v[216:217], v[218:219]
	v_pk_add_f32 v[72:73], v[216:217], v[72:73]
	v_lshlrev_b32_e32 v216, 16, v135
	v_and_b32_e32 v217, 0xffff0000, v135
	v_lshlrev_b32_e32 v218, 16, v139
	v_and_b32_e32 v219, 0xffff0000, v139
	v_pk_add_f32 v[216:217], v[216:217], v[218:219]
	v_pk_add_f32 v[74:75], v[216:217], v[74:75]
	v_cvt_pk_bf16_f32 v132, v76, v77
	v_cvt_pk_bf16_f32 v133, v78, v79
	v_cvt_pk_bf16_f32 v134, v72, v73
	v_cvt_pk_bf16_f32 v135, v74, v75
	global_store_dwordx4 v[128:129], v[132:135], off
	v_lshlrev_b32_e32 v216, 16, v132
	v_and_b32_e32 v217, 0xffff0000, v132
	v_pk_add_f32 v[216:217], v[76:77], v[216:217] neg_lo:[0,1] neg_hi:[0,1]
	v_pk_mul_f32 v[228:229], v[76:77], v[76:77]
	v_cvt_pk_bf16_f32 v136, v216, v217
	v_lshlrev_b32_e32 v216, 16, v133
	v_and_b32_e32 v217, 0xffff0000, v133
	v_pk_add_f32 v[216:217], v[78:79], v[216:217] neg_lo:[0,1] neg_hi:[0,1]
	v_pk_fma_f32 v[228:229], v[78:79], v[78:79], v[228:229]
	v_cvt_pk_bf16_f32 v137, v216, v217
	v_lshlrev_b32_e32 v216, 16, v134
	v_and_b32_e32 v217, 0xffff0000, v134
	v_pk_add_f32 v[216:217], v[72:73], v[216:217] neg_lo:[0,1] neg_hi:[0,1]
	v_pk_fma_f32 v[228:229], v[72:73], v[72:73], v[228:229]
	v_cvt_pk_bf16_f32 v138, v216, v217
	v_lshlrev_b32_e32 v216, 16, v135
	v_and_b32_e32 v217, 0xffff0000, v135
	v_pk_add_f32 v[216:217], v[74:75], v[216:217] neg_lo:[0,1] neg_hi:[0,1]
	v_pk_fma_f32 v[228:229], v[74:75], v[74:75], v[228:229]
	v_cvt_pk_bf16_f32 v139, v216, v217
	global_store_dwordx4 v[130:131], v[136:139], off
	v_permlane16_swap_b32_e32 v68, v64
	v_permlane16_swap_b32_e32 v69, v65
	v_permlane16_swap_b32_e32 v70, v66
	v_permlane16_swap_b32_e32 v71, v67
	s_waitcnt vmcnt(21)
	v_lshlrev_b32_e32 v216, 16, v140
	v_and_b32_e32 v217, 0xffff0000, v140
	s_waitcnt vmcnt(20)
	v_lshlrev_b32_e32 v218, 16, v144
	v_and_b32_e32 v219, 0xffff0000, v144
	v_pk_add_f32 v[216:217], v[216:217], v[218:219]
	v_pk_add_f32 v[68:69], v[216:217], v[68:69]
	v_lshlrev_b32_e32 v216, 16, v141
	v_and_b32_e32 v217, 0xffff0000, v141
	v_lshlrev_b32_e32 v218, 16, v145
	v_and_b32_e32 v219, 0xffff0000, v145
	v_pk_add_f32 v[216:217], v[216:217], v[218:219]
	v_pk_add_f32 v[70:71], v[216:217], v[70:71]
	v_lshlrev_b32_e32 v216, 16, v142
	v_and_b32_e32 v217, 0xffff0000, v142
	v_lshlrev_b32_e32 v218, 16, v146
	v_and_b32_e32 v219, 0xffff0000, v146
	v_pk_add_f32 v[216:217], v[216:217], v[218:219]
	v_pk_add_f32 v[64:65], v[216:217], v[64:65]
	v_lshlrev_b32_e32 v216, 16, v143
	v_and_b32_e32 v217, 0xffff0000, v143
	v_lshlrev_b32_e32 v218, 16, v147
	v_and_b32_e32 v219, 0xffff0000, v147
	v_pk_add_f32 v[216:217], v[216:217], v[218:219]
	v_pk_add_f32 v[66:67], v[216:217], v[66:67]
	v_cvt_pk_bf16_f32 v140, v68, v69
	v_cvt_pk_bf16_f32 v141, v70, v71
	v_cvt_pk_bf16_f32 v142, v64, v65
	v_cvt_pk_bf16_f32 v143, v66, v67
	global_store_dwordx4 v[128:129], v[140:143], off offset:256
	v_lshlrev_b32_e32 v216, 16, v140
	v_and_b32_e32 v217, 0xffff0000, v140
	v_pk_add_f32 v[216:217], v[68:69], v[216:217] neg_lo:[0,1] neg_hi:[0,1]
	v_pk_fma_f32 v[228:229], v[68:69], v[68:69], v[228:229]
	v_cvt_pk_bf16_f32 v144, v216, v217
	v_lshlrev_b32_e32 v216, 16, v141
	v_and_b32_e32 v217, 0xffff0000, v141
	v_pk_add_f32 v[216:217], v[70:71], v[216:217] neg_lo:[0,1] neg_hi:[0,1]
	v_pk_fma_f32 v[228:229], v[70:71], v[70:71], v[228:229]
	v_cvt_pk_bf16_f32 v145, v216, v217
	v_lshlrev_b32_e32 v216, 16, v142
	v_and_b32_e32 v217, 0xffff0000, v142
	v_pk_add_f32 v[216:217], v[64:65], v[216:217] neg_lo:[0,1] neg_hi:[0,1]
	v_pk_fma_f32 v[228:229], v[64:65], v[64:65], v[228:229]
	v_cvt_pk_bf16_f32 v146, v216, v217
	v_lshlrev_b32_e32 v216, 16, v143
	v_and_b32_e32 v217, 0xffff0000, v143
	v_pk_add_f32 v[216:217], v[66:67], v[216:217] neg_lo:[0,1] neg_hi:[0,1]
	v_pk_fma_f32 v[228:229], v[66:67], v[66:67], v[228:229]
	v_cvt_pk_bf16_f32 v147, v216, v217
	global_store_dwordx4 v[130:131], v[144:147], off offset:256
	v_add_f32_e32 v230, v228, v229
	v_mov_b32_e32 v231, v230
	s_nop 1
	v_permlane16_swap_b32_e32 v231, v230
	v_add_f32_e32 v230, v230, v231
	v_mov_b32_e32 v231, v230
	s_nop 1
	v_permlane32_swap_b32_e32 v231, v230
	v_add_f32_e32 v230, v230, v231
	v_add_co_u32_e32 v174, vcc, 0x1800, v172
	v_addc_co_u32_e32 v175, vcc, 0, v173, vcc
	s_and_saveexec_b64 s[24:25], s[14:15]
	global_store_dword v[174:175], v230, off
	s_mov_b64 exec, s[24:25]
	v_add_co_u32_e32 v168, vcc, 0xa0000, v164
	v_addc_co_u32_e32 v169, vcc, 0, v165, vcc
	v_add_co_u32_e32 v170, vcc, 0xa0000, v166
	v_addc_co_u32_e32 v171, vcc, 0, v167, vcc
	global_load_dwordx4 v[132:135], v[168:169], off
	global_load_dwordx4 v[136:139], v[170:171], off
	global_load_dwordx4 v[140:143], v[168:169], off offset:256
	global_load_dwordx4 v[144:147], v[170:171], off offset:256
	v_add_co_u32_e32 v128, vcc, 0x80000, v164
	v_addc_co_u32_e32 v129, vcc, 0, v165, vcc
	v_add_co_u32_e32 v130, vcc, 0x80000, v166
	v_addc_co_u32_e32 v131, vcc, 0, v167, vcc
	v_permlane16_swap_b32_e32 v60, v56
	v_permlane16_swap_b32_e32 v61, v57
	v_permlane16_swap_b32_e32 v62, v58
	v_permlane16_swap_b32_e32 v63, v59
	s_waitcnt vmcnt(21)
	v_lshlrev_b32_e32 v216, 16, v148
	v_and_b32_e32 v217, 0xffff0000, v148
	s_waitcnt vmcnt(20)
	v_lshlrev_b32_e32 v218, 16, v152
	v_and_b32_e32 v219, 0xffff0000, v152
	v_pk_add_f32 v[216:217], v[216:217], v[218:219]
	v_pk_add_f32 v[60:61], v[216:217], v[60:61]
	v_lshlrev_b32_e32 v216, 16, v149
	v_and_b32_e32 v217, 0xffff0000, v149
	v_lshlrev_b32_e32 v218, 16, v153
	v_and_b32_e32 v219, 0xffff0000, v153
	v_pk_add_f32 v[216:217], v[216:217], v[218:219]
	v_pk_add_f32 v[62:63], v[216:217], v[62:63]
	v_lshlrev_b32_e32 v216, 16, v150
	v_and_b32_e32 v217, 0xffff0000, v150
	v_lshlrev_b32_e32 v218, 16, v154
	v_and_b32_e32 v219, 0xffff0000, v154
	v_pk_add_f32 v[216:217], v[216:217], v[218:219]
	v_pk_add_f32 v[56:57], v[216:217], v[56:57]
	v_lshlrev_b32_e32 v216, 16, v151
	v_and_b32_e32 v217, 0xffff0000, v151
	v_lshlrev_b32_e32 v218, 16, v155
	v_and_b32_e32 v219, 0xffff0000, v155
	v_pk_add_f32 v[216:217], v[216:217], v[218:219]
	v_pk_add_f32 v[58:59], v[216:217], v[58:59]
	v_cvt_pk_bf16_f32 v148, v60, v61
	v_cvt_pk_bf16_f32 v149, v62, v63
	v_cvt_pk_bf16_f32 v150, v56, v57
	v_cvt_pk_bf16_f32 v151, v58, v59
	global_store_dwordx4 v[128:129], v[148:151], off
	v_lshlrev_b32_e32 v216, 16, v148
	v_and_b32_e32 v217, 0xffff0000, v148
	v_pk_add_f32 v[216:217], v[60:61], v[216:217] neg_lo:[0,1] neg_hi:[0,1]
	v_pk_mul_f32 v[228:229], v[60:61], v[60:61]
	v_cvt_pk_bf16_f32 v152, v216, v217
	v_lshlrev_b32_e32 v216, 16, v149
	v_and_b32_e32 v217, 0xffff0000, v149
	v_pk_add_f32 v[216:217], v[62:63], v[216:217] neg_lo:[0,1] neg_hi:[0,1]
	v_pk_fma_f32 v[228:229], v[62:63], v[62:63], v[228:229]
	v_cvt_pk_bf16_f32 v153, v216, v217
	v_lshlrev_b32_e32 v216, 16, v150
	v_and_b32_e32 v217, 0xffff0000, v150
	v_pk_add_f32 v[216:217], v[56:57], v[216:217] neg_lo:[0,1] neg_hi:[0,1]
	v_pk_fma_f32 v[228:229], v[56:57], v[56:57], v[228:229]
	v_cvt_pk_bf16_f32 v154, v216, v217
	v_lshlrev_b32_e32 v216, 16, v151
	v_and_b32_e32 v217, 0xffff0000, v151
	v_pk_add_f32 v[216:217], v[58:59], v[216:217] neg_lo:[0,1] neg_hi:[0,1]
	v_pk_fma_f32 v[228:229], v[58:59], v[58:59], v[228:229]
	v_cvt_pk_bf16_f32 v155, v216, v217
	global_store_dwordx4 v[130:131], v[152:155], off
	v_permlane16_swap_b32_e32 v52, v48
	v_permlane16_swap_b32_e32 v53, v49
	v_permlane16_swap_b32_e32 v54, v50
	v_permlane16_swap_b32_e32 v55, v51
	s_waitcnt vmcnt(21)
	v_lshlrev_b32_e32 v216, 16, v156
	v_and_b32_e32 v217, 0xffff0000, v156
	s_waitcnt vmcnt(20)
	v_lshlrev_b32_e32 v218, 16, v160
	v_and_b32_e32 v219, 0xffff0000, v160
	v_pk_add_f32 v[216:217], v[216:217], v[218:219]
	v_pk_add_f32 v[52:53], v[216:217], v[52:53]
	v_lshlrev_b32_e32 v216, 16, v157
	v_and_b32_e32 v217, 0xffff0000, v157
	v_lshlrev_b32_e32 v218, 16, v161
	v_and_b32_e32 v219, 0xffff0000, v161
	v_pk_add_f32 v[216:217], v[216:217], v[218:219]
	v_pk_add_f32 v[54:55], v[216:217], v[54:55]
	v_lshlrev_b32_e32 v216, 16, v158
	v_and_b32_e32 v217, 0xffff0000, v158
	v_lshlrev_b32_e32 v218, 16, v162
	v_and_b32_e32 v219, 0xffff0000, v162
	v_pk_add_f32 v[216:217], v[216:217], v[218:219]
	v_pk_add_f32 v[48:49], v[216:217], v[48:49]
	v_lshlrev_b32_e32 v216, 16, v159
	v_and_b32_e32 v217, 0xffff0000, v159
	v_lshlrev_b32_e32 v218, 16, v163
	v_and_b32_e32 v219, 0xffff0000, v163
	v_pk_add_f32 v[216:217], v[216:217], v[218:219]
	v_pk_add_f32 v[50:51], v[216:217], v[50:51]
	v_cvt_pk_bf16_f32 v156, v52, v53
	v_cvt_pk_bf16_f32 v157, v54, v55
	v_cvt_pk_bf16_f32 v158, v48, v49
	v_cvt_pk_bf16_f32 v159, v50, v51
	global_store_dwordx4 v[128:129], v[156:159], off offset:256
	v_lshlrev_b32_e32 v216, 16, v156
	v_and_b32_e32 v217, 0xffff0000, v156
	v_pk_add_f32 v[216:217], v[52:53], v[216:217] neg_lo:[0,1] neg_hi:[0,1]
	v_pk_fma_f32 v[228:229], v[52:53], v[52:53], v[228:229]
	v_cvt_pk_bf16_f32 v160, v216, v217
	v_lshlrev_b32_e32 v216, 16, v157
	v_and_b32_e32 v217, 0xffff0000, v157
	v_pk_add_f32 v[216:217], v[54:55], v[216:217] neg_lo:[0,1] neg_hi:[0,1]
	v_pk_fma_f32 v[228:229], v[54:55], v[54:55], v[228:229]
	v_cvt_pk_bf16_f32 v161, v216, v217
	v_lshlrev_b32_e32 v216, 16, v158
	v_and_b32_e32 v217, 0xffff0000, v158
	v_pk_add_f32 v[216:217], v[48:49], v[216:217] neg_lo:[0,1] neg_hi:[0,1]
	v_pk_fma_f32 v[228:229], v[48:49], v[48:49], v[228:229]
	v_cvt_pk_bf16_f32 v162, v216, v217
	v_lshlrev_b32_e32 v216, 16, v159
	v_and_b32_e32 v217, 0xffff0000, v159
	v_pk_add_f32 v[216:217], v[50:51], v[216:217] neg_lo:[0,1] neg_hi:[0,1]
	v_pk_fma_f32 v[228:229], v[50:51], v[50:51], v[228:229]
	v_cvt_pk_bf16_f32 v163, v216, v217
	global_store_dwordx4 v[130:131], v[160:163], off offset:256
	v_add_f32_e32 v230, v228, v229
	v_mov_b32_e32 v231, v230
	s_nop 1
	v_permlane16_swap_b32_e32 v231, v230
	v_add_f32_e32 v230, v230, v231
	v_mov_b32_e32 v231, v230
	s_nop 1
	v_permlane32_swap_b32_e32 v231, v230
	v_add_f32_e32 v230, v230, v231
	v_add_co_u32_e32 v174, vcc, 0x4000, v172
	v_addc_co_u32_e32 v175, vcc, 0, v173, vcc
	s_and_saveexec_b64 s[24:25], s[14:15]
	global_store_dword v[174:175], v230, off
	s_mov_b64 exec, s[24:25]
	v_add_co_u32_e32 v168, vcc, 0xb0000, v164
	v_addc_co_u32_e32 v169, vcc, 0, v165, vcc
	v_add_co_u32_e32 v170, vcc, 0xb0000, v166
	v_addc_co_u32_e32 v171, vcc, 0, v167, vcc
	global_load_dwordx4 v[148:151], v[168:169], off
	global_load_dwordx4 v[152:155], v[170:171], off
	global_load_dwordx4 v[156:159], v[168:169], off offset:256
	global_load_dwordx4 v[160:163], v[170:171], off offset:256
	v_add_co_u32_e32 v128, vcc, 0x90000, v164
	v_addc_co_u32_e32 v129, vcc, 0, v165, vcc
	v_add_co_u32_e32 v130, vcc, 0x90000, v166
	v_addc_co_u32_e32 v131, vcc, 0, v167, vcc
	v_permlane16_swap_b32_e32 v44, v40
	v_permlane16_swap_b32_e32 v45, v41
	v_permlane16_swap_b32_e32 v46, v42
	v_permlane16_swap_b32_e32 v47, v43
	s_waitcnt vmcnt(21)
	v_lshlrev_b32_e32 v216, 16, v200
	v_and_b32_e32 v217, 0xffff0000, v200
	s_waitcnt vmcnt(20)
	v_lshlrev_b32_e32 v218, 16, v204
	v_and_b32_e32 v219, 0xffff0000, v204
	v_pk_add_f32 v[216:217], v[216:217], v[218:219]
	v_pk_add_f32 v[44:45], v[216:217], v[44:45]
	v_lshlrev_b32_e32 v216, 16, v201
	v_and_b32_e32 v217, 0xffff0000, v201
	v_lshlrev_b32_e32 v218, 16, v205
	v_and_b32_e32 v219, 0xffff0000, v205
	v_pk_add_f32 v[216:217], v[216:217], v[218:219]
	v_pk_add_f32 v[46:47], v[216:217], v[46:47]
	v_lshlrev_b32_e32 v216, 16, v202
	v_and_b32_e32 v217, 0xffff0000, v202
	v_lshlrev_b32_e32 v218, 16, v206
	v_and_b32_e32 v219, 0xffff0000, v206
	v_pk_add_f32 v[216:217], v[216:217], v[218:219]
	v_pk_add_f32 v[40:41], v[216:217], v[40:41]
	v_lshlrev_b32_e32 v216, 16, v203
	v_and_b32_e32 v217, 0xffff0000, v203
	v_lshlrev_b32_e32 v218, 16, v207
	v_and_b32_e32 v219, 0xffff0000, v207
	v_pk_add_f32 v[216:217], v[216:217], v[218:219]
	v_pk_add_f32 v[42:43], v[216:217], v[42:43]
	v_cvt_pk_bf16_f32 v200, v44, v45
	v_cvt_pk_bf16_f32 v201, v46, v47
	v_cvt_pk_bf16_f32 v202, v40, v41
	v_cvt_pk_bf16_f32 v203, v42, v43
	global_store_dwordx4 v[128:129], v[200:203], off
	v_lshlrev_b32_e32 v216, 16, v200
	v_and_b32_e32 v217, 0xffff0000, v200
	v_pk_add_f32 v[216:217], v[44:45], v[216:217] neg_lo:[0,1] neg_hi:[0,1]
	v_pk_mul_f32 v[228:229], v[44:45], v[44:45]
	v_cvt_pk_bf16_f32 v204, v216, v217
	v_lshlrev_b32_e32 v216, 16, v201
	v_and_b32_e32 v217, 0xffff0000, v201
	v_pk_add_f32 v[216:217], v[46:47], v[216:217] neg_lo:[0,1] neg_hi:[0,1]
	v_pk_fma_f32 v[228:229], v[46:47], v[46:47], v[228:229]
	v_cvt_pk_bf16_f32 v205, v216, v217
	v_lshlrev_b32_e32 v216, 16, v202
	v_and_b32_e32 v217, 0xffff0000, v202
	v_pk_add_f32 v[216:217], v[40:41], v[216:217] neg_lo:[0,1] neg_hi:[0,1]
	v_pk_fma_f32 v[228:229], v[40:41], v[40:41], v[228:229]
	v_cvt_pk_bf16_f32 v206, v216, v217
	v_lshlrev_b32_e32 v216, 16, v203
	v_and_b32_e32 v217, 0xffff0000, v203
	v_pk_add_f32 v[216:217], v[42:43], v[216:217] neg_lo:[0,1] neg_hi:[0,1]
	v_pk_fma_f32 v[228:229], v[42:43], v[42:43], v[228:229]
	v_cvt_pk_bf16_f32 v207, v216, v217
	global_store_dwordx4 v[130:131], v[204:207], off
	v_permlane16_swap_b32_e32 v36, v32
	v_permlane16_swap_b32_e32 v37, v33
	v_permlane16_swap_b32_e32 v38, v34
	v_permlane16_swap_b32_e32 v39, v35
	s_waitcnt vmcnt(21)
	v_lshlrev_b32_e32 v216, 16, v208
	v_and_b32_e32 v217, 0xffff0000, v208
	s_waitcnt vmcnt(20)
	v_lshlrev_b32_e32 v218, 16, v212
	v_and_b32_e32 v219, 0xffff0000, v212
	v_pk_add_f32 v[216:217], v[216:217], v[218:219]
	v_pk_add_f32 v[36:37], v[216:217], v[36:37]
	v_lshlrev_b32_e32 v216, 16, v209
	v_and_b32_e32 v217, 0xffff0000, v209
	v_lshlrev_b32_e32 v218, 16, v213
	v_and_b32_e32 v219, 0xffff0000, v213
	v_pk_add_f32 v[216:217], v[216:217], v[218:219]
	v_pk_add_f32 v[38:39], v[216:217], v[38:39]
	v_lshlrev_b32_e32 v216, 16, v210
	v_and_b32_e32 v217, 0xffff0000, v210
	v_lshlrev_b32_e32 v218, 16, v214
	v_and_b32_e32 v219, 0xffff0000, v214
	v_pk_add_f32 v[216:217], v[216:217], v[218:219]
	v_pk_add_f32 v[32:33], v[216:217], v[32:33]
	v_lshlrev_b32_e32 v216, 16, v211
	v_and_b32_e32 v217, 0xffff0000, v211
	v_lshlrev_b32_e32 v218, 16, v215
	v_and_b32_e32 v219, 0xffff0000, v215
	v_pk_add_f32 v[216:217], v[216:217], v[218:219]
	v_pk_add_f32 v[34:35], v[216:217], v[34:35]
	v_cvt_pk_bf16_f32 v208, v36, v37
	v_cvt_pk_bf16_f32 v209, v38, v39
	v_cvt_pk_bf16_f32 v210, v32, v33
	v_cvt_pk_bf16_f32 v211, v34, v35
	global_store_dwordx4 v[128:129], v[208:211], off offset:256
	v_lshlrev_b32_e32 v216, 16, v208
	v_and_b32_e32 v217, 0xffff0000, v208
	v_pk_add_f32 v[216:217], v[36:37], v[216:217] neg_lo:[0,1] neg_hi:[0,1]
	v_pk_fma_f32 v[228:229], v[36:37], v[36:37], v[228:229]
	v_cvt_pk_bf16_f32 v212, v216, v217
	v_lshlrev_b32_e32 v216, 16, v209
	v_and_b32_e32 v217, 0xffff0000, v209
	v_pk_add_f32 v[216:217], v[38:39], v[216:217] neg_lo:[0,1] neg_hi:[0,1]
	v_pk_fma_f32 v[228:229], v[38:39], v[38:39], v[228:229]
	v_cvt_pk_bf16_f32 v213, v216, v217
	v_lshlrev_b32_e32 v216, 16, v210
	v_and_b32_e32 v217, 0xffff0000, v210
	v_pk_add_f32 v[216:217], v[32:33], v[216:217] neg_lo:[0,1] neg_hi:[0,1]
	v_pk_fma_f32 v[228:229], v[32:33], v[32:33], v[228:229]
	v_cvt_pk_bf16_f32 v214, v216, v217
	v_lshlrev_b32_e32 v216, 16, v211
	v_and_b32_e32 v217, 0xffff0000, v211
	v_pk_add_f32 v[216:217], v[34:35], v[216:217] neg_lo:[0,1] neg_hi:[0,1]
	v_pk_fma_f32 v[228:229], v[34:35], v[34:35], v[228:229]
	v_cvt_pk_bf16_f32 v215, v216, v217
	global_store_dwordx4 v[130:131], v[212:215], off offset:256
	v_add_f32_e32 v230, v228, v229
	v_mov_b32_e32 v231, v230
	s_nop 1
	v_permlane16_swap_b32_e32 v231, v230
	v_add_f32_e32 v230, v230, v231
	v_mov_b32_e32 v231, v230
	s_nop 1
	v_permlane32_swap_b32_e32 v231, v230
	v_add_f32_e32 v230, v230, v231
	v_add_co_u32_e32 v174, vcc, 0x4800, v172
	v_addc_co_u32_e32 v175, vcc, 0, v173, vcc
	s_and_saveexec_b64 s[24:25], s[14:15]
	global_store_dword v[174:175], v230, off
	s_mov_b64 exec, s[24:25]
	v_add_co_u32_e32 v128, vcc, 0xa0000, v164
	v_addc_co_u32_e32 v129, vcc, 0, v165, vcc
	v_add_co_u32_e32 v130, vcc, 0xa0000, v166
	v_addc_co_u32_e32 v131, vcc, 0, v167, vcc
	v_permlane16_swap_b32_e32 v28, v24
	v_permlane16_swap_b32_e32 v29, v25
	v_permlane16_swap_b32_e32 v30, v26
	v_permlane16_swap_b32_e32 v31, v27
	s_waitcnt vmcnt(17)
	v_lshlrev_b32_e32 v216, 16, v132
	v_and_b32_e32 v217, 0xffff0000, v132
	s_waitcnt vmcnt(16)
	v_lshlrev_b32_e32 v218, 16, v136
	v_and_b32_e32 v219, 0xffff0000, v136
	v_pk_add_f32 v[216:217], v[216:217], v[218:219]
	v_pk_add_f32 v[28:29], v[216:217], v[28:29]
	v_lshlrev_b32_e32 v216, 16, v133
	v_and_b32_e32 v217, 0xffff0000, v133
	v_lshlrev_b32_e32 v218, 16, v137
	v_and_b32_e32 v219, 0xffff0000, v137
	v_pk_add_f32 v[216:217], v[216:217], v[218:219]
	v_pk_add_f32 v[30:31], v[216:217], v[30:31]
	v_lshlrev_b32_e32 v216, 16, v134
	v_and_b32_e32 v217, 0xffff0000, v134
	v_lshlrev_b32_e32 v218, 16, v138
	v_and_b32_e32 v219, 0xffff0000, v138
	v_pk_add_f32 v[216:217], v[216:217], v[218:219]
	v_pk_add_f32 v[24:25], v[216:217], v[24:25]
	v_lshlrev_b32_e32 v216, 16, v135
	v_and_b32_e32 v217, 0xffff0000, v135
	v_lshlrev_b32_e32 v218, 16, v139
	v_and_b32_e32 v219, 0xffff0000, v139
	v_pk_add_f32 v[216:217], v[216:217], v[218:219]
	v_pk_add_f32 v[26:27], v[216:217], v[26:27]
	v_cvt_pk_bf16_f32 v132, v28, v29
	v_cvt_pk_bf16_f32 v133, v30, v31
	v_cvt_pk_bf16_f32 v134, v24, v25
	v_cvt_pk_bf16_f32 v135, v26, v27
	global_store_dwordx4 v[128:129], v[132:135], off
	v_lshlrev_b32_e32 v216, 16, v132
	v_and_b32_e32 v217, 0xffff0000, v132
	v_pk_add_f32 v[216:217], v[28:29], v[216:217] neg_lo:[0,1] neg_hi:[0,1]
	v_pk_mul_f32 v[228:229], v[28:29], v[28:29]
	v_cvt_pk_bf16_f32 v136, v216, v217
	v_lshlrev_b32_e32 v216, 16, v133
	v_and_b32_e32 v217, 0xffff0000, v133
	v_pk_add_f32 v[216:217], v[30:31], v[216:217] neg_lo:[0,1] neg_hi:[0,1]
	v_pk_fma_f32 v[228:229], v[30:31], v[30:31], v[228:229]
	v_cvt_pk_bf16_f32 v137, v216, v217
	v_lshlrev_b32_e32 v216, 16, v134
	v_and_b32_e32 v217, 0xffff0000, v134
	v_pk_add_f32 v[216:217], v[24:25], v[216:217] neg_lo:[0,1] neg_hi:[0,1]
	v_pk_fma_f32 v[228:229], v[24:25], v[24:25], v[228:229]
	v_cvt_pk_bf16_f32 v138, v216, v217
	v_lshlrev_b32_e32 v216, 16, v135
	v_and_b32_e32 v217, 0xffff0000, v135
	v_pk_add_f32 v[216:217], v[26:27], v[216:217] neg_lo:[0,1] neg_hi:[0,1]
	v_pk_fma_f32 v[228:229], v[26:27], v[26:27], v[228:229]
	v_cvt_pk_bf16_f32 v139, v216, v217
	global_store_dwordx4 v[130:131], v[136:139], off
	v_permlane16_swap_b32_e32 v20, v16
	v_permlane16_swap_b32_e32 v21, v17
	v_permlane16_swap_b32_e32 v22, v18
	v_permlane16_swap_b32_e32 v23, v19
	s_waitcnt vmcnt(17)
	v_lshlrev_b32_e32 v216, 16, v140
	v_and_b32_e32 v217, 0xffff0000, v140
	s_waitcnt vmcnt(16)
	v_lshlrev_b32_e32 v218, 16, v144
	v_and_b32_e32 v219, 0xffff0000, v144
	v_pk_add_f32 v[216:217], v[216:217], v[218:219]
	v_pk_add_f32 v[20:21], v[216:217], v[20:21]
	v_lshlrev_b32_e32 v216, 16, v141
	v_and_b32_e32 v217, 0xffff0000, v141
	v_lshlrev_b32_e32 v218, 16, v145
	v_and_b32_e32 v219, 0xffff0000, v145
	v_pk_add_f32 v[216:217], v[216:217], v[218:219]
	v_pk_add_f32 v[22:23], v[216:217], v[22:23]
	v_lshlrev_b32_e32 v216, 16, v142
	v_and_b32_e32 v217, 0xffff0000, v142
	v_lshlrev_b32_e32 v218, 16, v146
	v_and_b32_e32 v219, 0xffff0000, v146
	v_pk_add_f32 v[216:217], v[216:217], v[218:219]
	v_pk_add_f32 v[16:17], v[216:217], v[16:17]
	v_lshlrev_b32_e32 v216, 16, v143
	v_and_b32_e32 v217, 0xffff0000, v143
	v_lshlrev_b32_e32 v218, 16, v147
	v_and_b32_e32 v219, 0xffff0000, v147
	v_pk_add_f32 v[216:217], v[216:217], v[218:219]
	v_pk_add_f32 v[18:19], v[216:217], v[18:19]
	v_cvt_pk_bf16_f32 v140, v20, v21
	v_cvt_pk_bf16_f32 v141, v22, v23
	v_cvt_pk_bf16_f32 v142, v16, v17
	v_cvt_pk_bf16_f32 v143, v18, v19
	global_store_dwordx4 v[128:129], v[140:143], off offset:256
	v_lshlrev_b32_e32 v216, 16, v140
	v_and_b32_e32 v217, 0xffff0000, v140
	v_pk_add_f32 v[216:217], v[20:21], v[216:217] neg_lo:[0,1] neg_hi:[0,1]
	v_pk_fma_f32 v[228:229], v[20:21], v[20:21], v[228:229]
	v_cvt_pk_bf16_f32 v144, v216, v217
	v_lshlrev_b32_e32 v216, 16, v141
	v_and_b32_e32 v217, 0xffff0000, v141
	v_pk_add_f32 v[216:217], v[22:23], v[216:217] neg_lo:[0,1] neg_hi:[0,1]
	v_pk_fma_f32 v[228:229], v[22:23], v[22:23], v[228:229]
	v_cvt_pk_bf16_f32 v145, v216, v217
	v_lshlrev_b32_e32 v216, 16, v142
	v_and_b32_e32 v217, 0xffff0000, v142
	v_pk_add_f32 v[216:217], v[16:17], v[216:217] neg_lo:[0,1] neg_hi:[0,1]
	v_pk_fma_f32 v[228:229], v[16:17], v[16:17], v[228:229]
	v_cvt_pk_bf16_f32 v146, v216, v217
	v_lshlrev_b32_e32 v216, 16, v143
	v_and_b32_e32 v217, 0xffff0000, v143
	v_pk_add_f32 v[216:217], v[18:19], v[216:217] neg_lo:[0,1] neg_hi:[0,1]
	v_pk_fma_f32 v[228:229], v[18:19], v[18:19], v[228:229]
	v_cvt_pk_bf16_f32 v147, v216, v217
	global_store_dwordx4 v[130:131], v[144:147], off offset:256
	v_add_f32_e32 v230, v228, v229
	v_mov_b32_e32 v231, v230
	s_nop 1
	v_permlane16_swap_b32_e32 v231, v230
	v_add_f32_e32 v230, v230, v231
	v_mov_b32_e32 v231, v230
	s_nop 1
	v_permlane32_swap_b32_e32 v231, v230
	v_add_f32_e32 v230, v230, v231
	v_add_co_u32_e32 v174, vcc, 0x5000, v172
	v_addc_co_u32_e32 v175, vcc, 0, v173, vcc
	s_and_saveexec_b64 s[24:25], s[14:15]
	global_store_dword v[174:175], v230, off
	s_mov_b64 exec, s[24:25]
	v_add_co_u32_e32 v128, vcc, 0xb0000, v164
	v_addc_co_u32_e32 v129, vcc, 0, v165, vcc
	v_add_co_u32_e32 v130, vcc, 0xb0000, v166
	v_addc_co_u32_e32 v131, vcc, 0, v167, vcc
	v_permlane16_swap_b32_e32 v12, v8
	v_permlane16_swap_b32_e32 v13, v9
	v_permlane16_swap_b32_e32 v14, v10
	v_permlane16_swap_b32_e32 v15, v11
	s_waitcnt vmcnt(13)
	v_lshlrev_b32_e32 v216, 16, v148
	v_and_b32_e32 v217, 0xffff0000, v148
	s_waitcnt vmcnt(12)
	v_lshlrev_b32_e32 v218, 16, v152
	v_and_b32_e32 v219, 0xffff0000, v152
	v_pk_add_f32 v[216:217], v[216:217], v[218:219]
	v_pk_add_f32 v[12:13], v[216:217], v[12:13]
	v_lshlrev_b32_e32 v216, 16, v149
	v_and_b32_e32 v217, 0xffff0000, v149
	v_lshlrev_b32_e32 v218, 16, v153
	v_and_b32_e32 v219, 0xffff0000, v153
	v_pk_add_f32 v[216:217], v[216:217], v[218:219]
	v_pk_add_f32 v[14:15], v[216:217], v[14:15]
	v_lshlrev_b32_e32 v216, 16, v150
	v_and_b32_e32 v217, 0xffff0000, v150
	v_lshlrev_b32_e32 v218, 16, v154
	v_and_b32_e32 v219, 0xffff0000, v154
	v_pk_add_f32 v[216:217], v[216:217], v[218:219]
	v_pk_add_f32 v[8:9], v[216:217], v[8:9]
	v_lshlrev_b32_e32 v216, 16, v151
	v_and_b32_e32 v217, 0xffff0000, v151
	v_lshlrev_b32_e32 v218, 16, v155
	v_and_b32_e32 v219, 0xffff0000, v155
	v_pk_add_f32 v[216:217], v[216:217], v[218:219]
	v_pk_add_f32 v[10:11], v[216:217], v[10:11]
	v_cvt_pk_bf16_f32 v148, v12, v13
	v_cvt_pk_bf16_f32 v149, v14, v15
	v_cvt_pk_bf16_f32 v150, v8, v9
	v_cvt_pk_bf16_f32 v151, v10, v11
	global_store_dwordx4 v[128:129], v[148:151], off
	v_lshlrev_b32_e32 v216, 16, v148
	v_and_b32_e32 v217, 0xffff0000, v148
	v_pk_add_f32 v[216:217], v[12:13], v[216:217] neg_lo:[0,1] neg_hi:[0,1]
	v_pk_mul_f32 v[228:229], v[12:13], v[12:13]
	v_cvt_pk_bf16_f32 v152, v216, v217
	v_lshlrev_b32_e32 v216, 16, v149
	v_and_b32_e32 v217, 0xffff0000, v149
	v_pk_add_f32 v[216:217], v[14:15], v[216:217] neg_lo:[0,1] neg_hi:[0,1]
	v_pk_fma_f32 v[228:229], v[14:15], v[14:15], v[228:229]
	v_cvt_pk_bf16_f32 v153, v216, v217
	v_lshlrev_b32_e32 v216, 16, v150
	v_and_b32_e32 v217, 0xffff0000, v150
	v_pk_add_f32 v[216:217], v[8:9], v[216:217] neg_lo:[0,1] neg_hi:[0,1]
	v_pk_fma_f32 v[228:229], v[8:9], v[8:9], v[228:229]
	v_cvt_pk_bf16_f32 v154, v216, v217
	v_lshlrev_b32_e32 v216, 16, v151
	v_and_b32_e32 v217, 0xffff0000, v151
	v_pk_add_f32 v[216:217], v[10:11], v[216:217] neg_lo:[0,1] neg_hi:[0,1]
	v_pk_fma_f32 v[228:229], v[10:11], v[10:11], v[228:229]
	v_cvt_pk_bf16_f32 v155, v216, v217
	global_store_dwordx4 v[130:131], v[152:155], off
	v_permlane16_swap_b32_e32 v4, v0
	v_permlane16_swap_b32_e32 v5, v1
	v_permlane16_swap_b32_e32 v6, v2
	v_permlane16_swap_b32_e32 v7, v3
	s_waitcnt vmcnt(13)
	v_lshlrev_b32_e32 v216, 16, v156
	v_and_b32_e32 v217, 0xffff0000, v156
	s_waitcnt vmcnt(12)
	v_lshlrev_b32_e32 v218, 16, v160
	v_and_b32_e32 v219, 0xffff0000, v160
	v_pk_add_f32 v[216:217], v[216:217], v[218:219]
	v_pk_add_f32 v[4:5], v[216:217], v[4:5]
	v_lshlrev_b32_e32 v216, 16, v157
	v_and_b32_e32 v217, 0xffff0000, v157
	v_lshlrev_b32_e32 v218, 16, v161
	v_and_b32_e32 v219, 0xffff0000, v161
	v_pk_add_f32 v[216:217], v[216:217], v[218:219]
	v_pk_add_f32 v[6:7], v[216:217], v[6:7]
	v_lshlrev_b32_e32 v216, 16, v158
	v_and_b32_e32 v217, 0xffff0000, v158
	v_lshlrev_b32_e32 v218, 16, v162
	v_and_b32_e32 v219, 0xffff0000, v162
	v_pk_add_f32 v[216:217], v[216:217], v[218:219]
	v_pk_add_f32 v[0:1], v[216:217], v[0:1]
	v_lshlrev_b32_e32 v216, 16, v159
	v_and_b32_e32 v217, 0xffff0000, v159
	v_lshlrev_b32_e32 v218, 16, v163
	v_and_b32_e32 v219, 0xffff0000, v163
	v_pk_add_f32 v[216:217], v[216:217], v[218:219]
	v_pk_add_f32 v[2:3], v[216:217], v[2:3]
	v_cvt_pk_bf16_f32 v156, v4, v5
	v_cvt_pk_bf16_f32 v157, v6, v7
	v_cvt_pk_bf16_f32 v158, v0, v1
	v_cvt_pk_bf16_f32 v159, v2, v3
	global_store_dwordx4 v[128:129], v[156:159], off offset:256
	v_lshlrev_b32_e32 v216, 16, v156
	v_and_b32_e32 v217, 0xffff0000, v156
	v_pk_add_f32 v[216:217], v[4:5], v[216:217] neg_lo:[0,1] neg_hi:[0,1]
	v_pk_fma_f32 v[228:229], v[4:5], v[4:5], v[228:229]
	v_cvt_pk_bf16_f32 v160, v216, v217
	v_lshlrev_b32_e32 v216, 16, v157
	v_and_b32_e32 v217, 0xffff0000, v157
	v_pk_add_f32 v[216:217], v[6:7], v[216:217] neg_lo:[0,1] neg_hi:[0,1]
	v_pk_fma_f32 v[228:229], v[6:7], v[6:7], v[228:229]
	v_cvt_pk_bf16_f32 v161, v216, v217
	v_lshlrev_b32_e32 v216, 16, v158
	v_and_b32_e32 v217, 0xffff0000, v158
	v_pk_add_f32 v[216:217], v[0:1], v[216:217] neg_lo:[0,1] neg_hi:[0,1]
	v_pk_fma_f32 v[228:229], v[0:1], v[0:1], v[228:229]
	v_cvt_pk_bf16_f32 v162, v216, v217
	v_lshlrev_b32_e32 v216, 16, v159
	v_and_b32_e32 v217, 0xffff0000, v159
	v_pk_add_f32 v[216:217], v[2:3], v[216:217] neg_lo:[0,1] neg_hi:[0,1]
	v_pk_fma_f32 v[228:229], v[2:3], v[2:3], v[228:229]
	v_cvt_pk_bf16_f32 v163, v216, v217
	global_store_dwordx4 v[130:131], v[160:163], off offset:256
	v_add_f32_e32 v230, v228, v229
	v_mov_b32_e32 v231, v230
	s_nop 1
	v_permlane16_swap_b32_e32 v231, v230
	v_add_f32_e32 v230, v230, v231
	v_mov_b32_e32 v231, v230
	s_nop 1
	v_permlane32_swap_b32_e32 v231, v230
	v_add_f32_e32 v230, v230, v231
	v_add_co_u32_e32 v174, vcc, 0x5800, v172
	v_addc_co_u32_e32 v175, vcc, 0, v173, vcc
	s_and_saveexec_b64 s[24:25], s[14:15]
	global_store_dword v[174:175], v230, off
	s_mov_b64 exec, s[24:25]
	s_andn2_b64 vcc, exec, s[4:5]
	s_mov_b64 s[2:3], -1
	s_cbranch_vccnz .LBB0_42
	s_branch .LBB0_88
